# final norm: sample rows spread over all 256 workgroups (2 rows per workgroup) instead of the last 64 workgroups
# baseline (speedup 1.0000x reference)
.LBB0_1159:
	s_cmp_gt_i32 s88, 6
	s_cselect_b64 s[2:3], -1, 0
	s_xor_b64 s[0:1], s[0:1], -1
	s_or_b64 s[0:1], s[2:3], s[0:1]
	s_and_b64 vcc, exec, s[0:1]
	s_cbranch_vccnz .LBB0_1163
	v_readlane_b32 s0, v249, 0
	s_lshl_b32 s0, s0, 3
	v_lshrrev_b32_e32 v22, 6, v188
	s_lshl_b32 s2, s96, 3
	v_add_u32_e32 v0, s0, v22
	s_cmpk_eq_i32 s96, 0x100
	s_cbranch_scc1 .Lp6_new
	v_xad_u32 v16, v0, -1, s2
	s_branch .Lp6_m
.Lp6_new:
	s_lshr_b32 s3, s0, 2
	v_add_u32_e32 v16, s3, v22
	v_lshrrev_b32_e32 v17, 1, v22
	v_lshl_add_u32 v16, v17, 16, v16
.Lp6_m:
	s_movk_i32 s1, 0x200
	v_cmp_gt_i32_e32 vcc, s1, v16
	s_and_saveexec_b64 s[4:5], vcc
	s_cbranch_execz .LBB0_1163
	v_and_b32_e32 v0, 63, v188
	v_readlane_b32 s4, v249, 23
	v_lshlrev_b32_e32 v18, 4, v0
	v_readlane_b32 s18, v249, 37
	v_readlane_b32 s19, v249, 38
	s_nop 4
	global_load_dwordx4 v[0:3], v18, s[18:19]
	global_load_dwordx4 v[4:7], v18, s[18:19] offset:1024
	global_load_dwordx4 v[8:11], v18, s[18:19] offset:2048
	global_load_dwordx4 v[12:15], v18, s[18:19] offset:3072
	v_mbcnt_lo_u32_b32 v17, -1, 0
	v_mbcnt_hi_u32_b32 v17, -1, v17
	s_waitcnt lgkmcnt(0)
	v_and_b32_e32 v20, 64, v17
	v_add_u32_e32 v20, 64, v20
	v_xor_b32_e32 v21, 1, v17
	v_cmp_lt_i32_e32 vcc, v21, v20
	v_readlane_b32 s14, v249, 33
	v_readlane_b32 s15, v249, 34
	v_cndmask_b32_e32 v21, v17, v21, vcc
	v_lshlrev_b32_e32 v28, 2, v21
	v_xor_b32_e32 v21, 2, v17
	v_cmp_lt_i32_e32 vcc, v21, v20
	v_readlane_b32 s5, v249, 24
	v_readlane_b32 s6, v249, 25
	v_cndmask_b32_e32 v21, v17, v21, vcc
	v_lshlrev_b32_e32 v29, 2, v21
	v_xor_b32_e32 v21, 4, v17
	v_cmp_lt_i32_e32 vcc, v21, v20
	v_readlane_b32 s7, v249, 26
	v_readlane_b32 s8, v249, 27
	v_cndmask_b32_e32 v21, v17, v21, vcc
	v_lshlrev_b32_e32 v30, 2, v21
	v_xor_b32_e32 v21, 8, v17
	v_cmp_lt_i32_e32 vcc, v21, v20
	v_readlane_b32 s9, v249, 28
	v_readlane_b32 s10, v249, 29
	v_cndmask_b32_e32 v21, v17, v21, vcc
	v_lshlrev_b32_e32 v31, 2, v21
	v_xor_b32_e32 v21, 16, v17
	v_cmp_lt_i32_e32 vcc, v21, v20
	v_readlane_b32 s11, v249, 30
	v_readlane_b32 s12, v249, 31
	v_cndmask_b32_e32 v21, v17, v21, vcc
	v_lshlrev_b32_e32 v32, 2, v21
	v_xor_b32_e32 v21, 32, v17
	v_cmp_lt_i32_e32 vcc, v21, v20
	v_readlane_b32 s13, v249, 32
	v_readlane_b32 s16, v249, 35
	v_cndmask_b32_e32 v17, v17, v21, vcc
	v_lshlrev_b32_e32 v33, 2, v17
	v_ashrrev_i32_e32 v17, 31, v16
	v_lshlrev_b64 v[20:21], 12, v[16:17]
	v_add_u32_e32 v22, 0x10000, v16
	s_nop 0
	s_nop 0
	v_ashrrev_i32_e32 v23, 31, v22
	v_readlane_b32 s17, v249, 36
	s_mov_b64 s[14:15], s[18:19]
	s_ashr_i32 s3, s2, 31
	v_lshlrev_b64 v[22:23], 12, v[22:23]
	v_mov_b32_e32 v19, 0
	v_lshl_add_u64 v[20:21], s[30:31], 0, v[20:21]
	s_lshl_b64 s[4:5], s[2:3], 12
	v_lshl_add_u64 v[22:23], s[28:29], 0, v[22:23]
	s_mov_b64 s[6:7], 0
	s_mov_b32 s3, 0x2b400000
	s_mov_b32 s8, 0x2b600000
	s_mov_b32 s9, 0x2b800000
	s_mov_b32 s10, 0x2ba00000
	s_mov_b32 s11, 0x2bc00000
	s_mov_b32 s12, 0x2be00000
	s_brev_b32 s13, 52
	s_mov_b32 s14, 0x2c200000
	s_mov_b32 s15, 0x2c400000
	s_mov_b32 s16, 0x2c600000
	v_mov_b32_e32 v17, 0x358637bd
	s_movk_i32 s17, 0x1ff
